# all 9 grid barriers XCC-aware: census of workgroups per physical XCC posted at kernel entry (complete once wait_mod passes), last arriver of an XCC does the single L2 write-back and adds its census co
# speedup vs baseline: 1.0070x; 1.0049x over previous
; DI int tid_() { int t = threadIdx.x; asm volatile("" : "+v"(t)); return t; }
; DI void phase0a(const Params& p, char* smem) {
;   const int t = tid_();
;   const int nMod = 384, nPos = 288, nMisc = 3;
;   for (int it = blockIdx.x; it < nMod; it += gridDim.x) {
;     mod_item(p, it, smem);
;     __syncthreads();
;     if (t == 0) { __threadfence(); atomicAdd(p.modctr, 1u); }
; __global__ void __launch_bounds__(NTH, 2) mega_kernel(Params p) {
;   cg::grid_group grid = cg::this_grid();
;   __shared__ __attribute__((aligned(16))) char smem[SMEM_BYTES];
;     ...
;   phase0a(p, smem);
_Z11mega_kernel6Params:
	s_load_dword s3, s[0:1], 0x490
	s_add_u32 s4, s0, 0x490
	s_addc_u32 s5, s1, 0
	v_and_b32_e32 v220, 0x3ff, v0
	v_writelane_b32 v252, s4, 0
	v_mov_b32_e32 v2, v220
	v_cmp_eq_u32_e32 vcc, 0, v220
	s_and_b64 exec, exec, vcc
	s_cbranch_execz .Lcen_skip
	s_load_dwordx2 s[98:99], s[0:1], 0x158
	s_getreg_b32 s100, hwreg(HW_REG_XCC_ID, 0, 4)
	v_mov_b32_e32 v1, 1
	s_lshl_b32 s100, s100, 2
	v_mov_b32_e32 v3, s100
	s_waitcnt lgkmcnt(0)
	global_atomic_add v3, v1, s[98:99] offset:192
	s_waitcnt vmcnt(0)
.Lcen_skip:
	s_mov_b64 exec, -1
	s_cmpk_gt_i32 s2, 0x17f
	v_writelane_b32 v252, s5, 1
	s_cbranch_scc1 .LBB0_17
	s_load_dwordx2 s[14:15], s[0:1], 0x8
	s_load_dwordx4 s[8:11], s[0:1], 0x18
	s_load_dwordx2 s[16:17], s[0:1], 0x28
	s_load_dwordx2 s[18:19], s[0:1], 0xb8
	s_load_dwordx2 s[20:21], s[0:1], 0x158
	s_mov_b32 s13, 0
	v_cmp_eq_u32_e64 s[6:7], 0, v2
	s_movk_i32 s26, 0x6000
	s_waitcnt lgkmcnt(0)
	v_mov_b64_e32 v[4:5], s[10:11]
	v_mov_b32_e32 v7, 0
	s_movk_i32 s27, 0x1080
	s_movk_i32 s28, 0xe7f
	s_movk_i32 s29, 0x840
	s_movk_i32 s30, 0x210
	s_movk_i32 s31, 0x1800
	s_mov_b32 s33, s2
	s_branch .LBB0_3

; __global__ void __launch_bounds__(NTH, 2) mega_kernel(Params p) {
;     ...
;   grid.sync();
.LBB0_188:
	v_lshrrev_b32_e32 v1, 20, v0
	v_lshrrev_b32_e32 v0, 10, v0
	v_or_b32_e32 v0, v0, v1
	s_movk_i32 s4, 0x3ff
	v_and_or_b32 v0, v0, s4, v220
	v_cmp_eq_u32_e64 s[72:73], 0, v0
	s_waitcnt vmcnt(0) lgkmcnt(0)
	s_barrier
	s_and_saveexec_b64 s[4:5], s[72:73]
	s_cbranch_execz .LBB0_198
	s_load_dwordx2 s[6:7], s[0:1], 0x158
	s_load_dword s8, s[0:1], 0x490
	s_getreg_b32 s9, hwreg(HW_REG_XCC_ID, 0, 4)
	v_mov_b32_e32 v0, 0
	v_mov_b32_e32 v1, 1
	s_lshl_b32 s9, s9, 2
	v_mov_b32_e32 v3, s9
	s_waitcnt lgkmcnt(0)
	global_atomic_add v2, v3, v1, s[6:7] offset:160 sc0
	global_load_dword v3, v3, s[6:7] offset:192 sc1
	s_mul_i32 s8, s8, 1
	s_waitcnt vmcnt(0)
	v_add_u32_e32 v2, 1, v2
	v_mul_u32_u24_e32 v1, 1, v3
	v_cmp_ne_u32_e32 vcc, v1, v2
	s_cbranch_vccnz .Lgs1_wait
	buffer_wbl2 sc1
	s_waitcnt vmcnt(0)
	global_atomic_add v0, v3, s[6:7] offset:136
.Lgs1_wait:
	s_movk_i32 s11, 0x4000
.Lgs1_poll:
	global_load_dword v2, v0, s[6:7] offset:136 sc1
	s_waitcnt vmcnt(0)
	v_cmp_gt_u32_e32 vcc, s8, v2
	s_cbranch_vccz .Lgs1_done
	s_sleep 3
	s_sub_u32 s11, s11, 1
	s_cmp_lg_u32 s11, 0
	s_cbranch_scc1 .Lgs1_poll

; #define RUNPH(k, call) for (int rep_ = 0; rep_ < (((REPMASK) >> (k)) & 1) + 1; ++rep_) { call; grid.sync(); }
; __global__ void __launch_bounds__(NTH, 2) mega_kernel(Params p) {
;     ...
;   RUNPH(2, phase2(p, smem))
.LBB0_302:
	s_waitcnt vmcnt(0) lgkmcnt(0)
	s_barrier
	s_and_saveexec_b64 s[4:5], s[72:73]
	s_cbranch_execz .LBB0_312
	s_load_dwordx2 s[6:7], s[0:1], 0x158
	s_load_dword s8, s[0:1], 0x490
	s_getreg_b32 s9, hwreg(HW_REG_XCC_ID, 0, 4)
	v_mov_b32_e32 v0, 0
	v_mov_b32_e32 v1, 1
	s_lshl_b32 s9, s9, 2
	v_mov_b32_e32 v3, s9
	s_waitcnt lgkmcnt(0)
	global_atomic_add v2, v3, v1, s[6:7] offset:160 sc0
	global_load_dword v3, v3, s[6:7] offset:192 sc1
	s_mul_i32 s8, s8, 2
	s_waitcnt vmcnt(0)
	v_add_u32_e32 v2, 1, v2
	v_mul_u32_u24_e32 v1, 2, v3
	v_cmp_ne_u32_e32 vcc, v1, v2
	s_cbranch_vccnz .Lgs2_wait
	buffer_wbl2 sc1
	s_waitcnt vmcnt(0)
	global_atomic_add v0, v3, s[6:7] offset:136

; #define RUNPH(k, call) for (int rep_ = 0; rep_ < (((REPMASK) >> (k)) & 1) + 1; ++rep_) { call; grid.sync(); }
; __global__ void __launch_bounds__(NTH, 2) mega_kernel(Params p) {
;     ...
;   RUNPH(3, phase3(p, smem))
.LBB0_525:
	s_waitcnt vmcnt(0) lgkmcnt(0)
	s_barrier
	s_and_saveexec_b64 s[4:5], s[72:73]
	s_cbranch_execz .LBB0_535
	s_load_dwordx2 s[6:7], s[0:1], 0x158
	s_load_dword s8, s[0:1], 0x490
	s_getreg_b32 s9, hwreg(HW_REG_XCC_ID, 0, 4)
	v_mov_b32_e32 v0, 0
	v_mov_b32_e32 v1, 1
	s_lshl_b32 s9, s9, 2
	v_mov_b32_e32 v3, s9
	s_waitcnt lgkmcnt(0)
	global_atomic_add v2, v3, v1, s[6:7] offset:160 sc0
	global_load_dword v3, v3, s[6:7] offset:192 sc1
	s_mul_i32 s8, s8, 3
	s_waitcnt vmcnt(0)
	v_add_u32_e32 v2, 1, v2
	v_mul_u32_u24_e32 v1, 3, v3
	v_cmp_ne_u32_e32 vcc, v1, v2
	s_cbranch_vccnz .Lgs3_wait
	buffer_wbl2 sc1
	s_waitcnt vmcnt(0)
	global_atomic_add v0, v3, s[6:7] offset:136

; #define RUNPH(k, call) for (int rep_ = 0; rep_ < (((REPMASK) >> (k)) & 1) + 1; ++rep_) { call; grid.sync(); }
; __global__ void __launch_bounds__(NTH, 2) mega_kernel(Params p) {
;     ...
;   RUNPH(4, phase4(p, smem))
.LBB0_645:
	s_waitcnt vmcnt(0) lgkmcnt(0)
	s_barrier
	s_and_saveexec_b64 s[4:5], s[72:73]
	s_cbranch_execz .LBB0_655
	s_load_dwordx2 s[6:7], s[0:1], 0x158
	s_load_dword s8, s[0:1], 0x490
	s_getreg_b32 s9, hwreg(HW_REG_XCC_ID, 0, 4)
	v_mov_b32_e32 v0, 0
	v_mov_b32_e32 v1, 1
	s_lshl_b32 s9, s9, 2
	v_mov_b32_e32 v3, s9
	s_waitcnt lgkmcnt(0)
	global_atomic_add v2, v3, v1, s[6:7] offset:160 sc0
	global_load_dword v3, v3, s[6:7] offset:192 sc1
	s_mul_i32 s8, s8, 4
	s_waitcnt vmcnt(0)
	v_add_u32_e32 v2, 1, v2
	v_mul_u32_u24_e32 v1, 4, v3
	v_cmp_ne_u32_e32 vcc, v1, v2
	s_cbranch_vccnz .Lgs4_wait
	buffer_wbl2 sc1
	s_waitcnt vmcnt(0)
	global_atomic_add v0, v3, s[6:7] offset:136

; #define RUNPH(k, call) for (int rep_ = 0; rep_ < (((REPMASK) >> (k)) & 1) + 1; ++rep_) { call; grid.sync(); }
; __global__ void __launch_bounds__(NTH, 2) mega_kernel(Params p) {
;     ...
;   RUNPH(5, phase5(p, smem))
.LBB0_882:
	s_waitcnt vmcnt(0) lgkmcnt(0)
	s_barrier
	s_and_saveexec_b64 s[4:5], s[72:73]
	s_cbranch_execz .LBB0_892
	s_load_dwordx2 s[6:7], s[0:1], 0x158
	s_load_dword s8, s[0:1], 0x490
	s_getreg_b32 s9, hwreg(HW_REG_XCC_ID, 0, 4)
	v_mov_b32_e32 v0, 0
	v_mov_b32_e32 v1, 1
	s_lshl_b32 s9, s9, 2
	v_mov_b32_e32 v3, s9
	s_waitcnt lgkmcnt(0)
	global_atomic_add v2, v3, v1, s[6:7] offset:160 sc0
	global_load_dword v3, v3, s[6:7] offset:192 sc1
	s_mul_i32 s8, s8, 5
	s_waitcnt vmcnt(0)
	v_add_u32_e32 v2, 1, v2
	v_mul_u32_u24_e32 v1, 5, v3
	v_cmp_ne_u32_e32 vcc, v1, v2
	s_cbranch_vccnz .Lgs5_wait
	buffer_wbl2 sc1
	s_waitcnt vmcnt(0)
	global_atomic_add v0, v3, s[6:7] offset:136

; #define RUNPH(k, call) for (int rep_ = 0; rep_ < (((REPMASK) >> (k)) & 1) + 1; ++rep_) { call; grid.sync(); }
; __global__ void __launch_bounds__(NTH, 2) mega_kernel(Params p) {
;     ...
;   RUNPH(6, phase6(p, smem))
.LBB0_929:
	s_waitcnt vmcnt(0) lgkmcnt(0)
	s_barrier
	s_and_saveexec_b64 s[4:5], s[72:73]
	s_cbranch_execz .LBB0_939
	s_load_dwordx2 s[6:7], s[0:1], 0x158
	s_load_dword s8, s[0:1], 0x490
	s_getreg_b32 s9, hwreg(HW_REG_XCC_ID, 0, 4)
	v_mov_b32_e32 v0, 0
	v_mov_b32_e32 v1, 1
	s_lshl_b32 s9, s9, 2
	v_mov_b32_e32 v3, s9
	s_waitcnt lgkmcnt(0)
	global_atomic_add v2, v3, v1, s[6:7] offset:160 sc0
	global_load_dword v3, v3, s[6:7] offset:192 sc1
	s_mul_i32 s8, s8, 6
	s_waitcnt vmcnt(0)
	v_add_u32_e32 v2, 1, v2
	v_mul_u32_u24_e32 v1, 6, v3
	v_cmp_ne_u32_e32 vcc, v1, v2
	s_cbranch_vccnz .Lgs6_wait
	buffer_wbl2 sc1
	s_waitcnt vmcnt(0)
	global_atomic_add v0, v3, s[6:7] offset:136

; #define RUNPH(k, call) for (int rep_ = 0; rep_ < (((REPMASK) >> (k)) & 1) + 1; ++rep_) { call; grid.sync(); }
; __global__ void __launch_bounds__(NTH, 2) mega_kernel(Params p) {
;     ...
;   RUNPH(7, phase7(p, smem))
.LBB0_968:
	s_or_b64 exec, exec, s[18:19]
	s_waitcnt vmcnt(0) lgkmcnt(0)
	s_barrier
	s_and_saveexec_b64 s[4:5], s[72:73]
	s_cbranch_execz .LBB0_978
	s_load_dwordx2 s[6:7], s[0:1], 0x158
	s_load_dword s8, s[0:1], 0x490
	s_getreg_b32 s9, hwreg(HW_REG_XCC_ID, 0, 4)
	v_mov_b32_e32 v0, 0
	v_mov_b32_e32 v1, 1
	s_lshl_b32 s9, s9, 2
	v_mov_b32_e32 v3, s9
	s_waitcnt lgkmcnt(0)
	global_atomic_add v2, v3, v1, s[6:7] offset:160 sc0
	global_load_dword v3, v3, s[6:7] offset:192 sc1
	s_mul_i32 s8, s8, 7
	s_waitcnt vmcnt(0)
	v_add_u32_e32 v2, 1, v2
	v_mul_u32_u24_e32 v1, 7, v3
	v_cmp_ne_u32_e32 vcc, v1, v2
	s_cbranch_vccnz .Lgs7_wait
	buffer_wbl2 sc1
	s_waitcnt vmcnt(0)
	global_atomic_add v0, v3, s[6:7] offset:136

; #define RUNPH(k, call) for (int rep_ = 0; rep_ < (((REPMASK) >> (k)) & 1) + 1; ++rep_) { call; grid.sync(); }
; __global__ void __launch_bounds__(NTH, 2) mega_kernel(Params p) {
;     ...
;   RUNPH(8, phase8(p))
.LBB0_1175:
	s_or_b64 exec, exec, s[88:89]
	s_waitcnt vmcnt(0) lgkmcnt(0)
	s_barrier
	s_and_saveexec_b64 s[4:5], s[72:73]
	s_cbranch_execz .LBB0_1185
	s_load_dwordx2 s[6:7], s[0:1], 0x158
	s_load_dword s8, s[0:1], 0x490
	s_getreg_b32 s9, hwreg(HW_REG_XCC_ID, 0, 4)
	v_mov_b32_e32 v0, 0
	v_mov_b32_e32 v1, 1
	s_lshl_b32 s9, s9, 2
	v_mov_b32_e32 v3, s9
	s_waitcnt lgkmcnt(0)
	global_atomic_add v2, v3, v1, s[6:7] offset:160 sc0
	global_load_dword v3, v3, s[6:7] offset:192 sc1
	s_mul_i32 s8, s8, 8
	s_waitcnt vmcnt(0)
	v_add_u32_e32 v2, 1, v2
	v_mul_u32_u24_e32 v1, 8, v3
	v_cmp_ne_u32_e32 vcc, v1, v2
	s_cbranch_vccnz .Lgs8_wait
	buffer_wbl2 sc1
	s_waitcnt vmcnt(0)
	global_atomic_add v0, v3, s[6:7] offset:136

; __global__ void __launch_bounds__(NTH, 2) mega_kernel(Params p) {
;     ...
;   grid.sync();
.LBB0_1372:
	s_waitcnt vmcnt(0) lgkmcnt(0)
	s_barrier
	s_and_saveexec_b64 s[2:3], s[72:73]
	s_cbranch_execz .LBB0_1382
	s_load_dwordx2 s[6:7], s[0:1], 0x158
	s_load_dword s8, s[0:1], 0x490
	s_getreg_b32 s9, hwreg(HW_REG_XCC_ID, 0, 4)
	v_mov_b32_e32 v0, 0
	v_mov_b32_e32 v1, 1
	s_lshl_b32 s9, s9, 2
	v_mov_b32_e32 v3, s9
	s_waitcnt lgkmcnt(0)
	global_atomic_add v2, v3, v1, s[6:7] offset:160 sc0
	global_load_dword v3, v3, s[6:7] offset:192 sc1
	s_mul_i32 s8, s8, 9
	s_waitcnt vmcnt(0)
	v_add_u32_e32 v2, 1, v2
	v_mul_u32_u24_e32 v1, 9, v3
	v_cmp_ne_u32_e32 vcc, v1, v2
	s_cbranch_vccnz .Lgs9_wait
	buffer_wbl2 sc1
	s_waitcnt vmcnt(0)
	global_atomic_add v0, v3, s[6:7] offset:136
